# G1: nt on the A-operand LDS-DMA loads (read-through stream should not evict the shared B tile from L2)
# baseline (speedup 1.0000x reference)
; #define PG8_STAGE(bufoff, gbase, voff) do { const char* _gb = (const char*)(gbase); asm volatile("" : "+s"(_gb)); _Pragma("unroll") for (int _i = 0; _i < 2; ++_i) \
;         __builtin_amdgcn_global_load_lds((const unsigned*)(_gb + (voff)[_i]), (LAS unsigned*)(lds + (bufoff) + ldsw + _i * 8192), 16, 0, 0); } while (0)
; #define PG8_LDA(dst, b, h) do { _Pragma("unroll") for (int m = 0; m < 4; ++m) _Pragma("unroll") for (int k = 0; k < 2; ++k) dst[m][k] = *(const LAS bf16x8*)(lds + PG8_SA(b, h) + aoff + m * 2048 + k * 1024); } while (0)
; #define PG8_LDB(dst, b, h) do { _Pragma("unroll") for (int n = 0; n < 2; ++n) _Pragma("unroll") for (int k = 0; k < 2; ++k) dst[n][k] = *(const LAS bf16x8*)(lds + PG8_SB(b, h) + boff + n * 2048 + k * 1024); } while (0)
; #define PG8_MMA(ai, bj, At, Bt) do { __builtin_amdgcn_s_setprio(1); _Pragma("unroll") for (int m = 0; m < 4; ++m) _Pragma("unroll") for (int n = 0; n < 2; ++n) _Pragma("unroll") for (int k = 0; k < 2; ++k) \
;         acc[ai][bj][m][n] = __builtin_amdgcn_mfma_f32_16x16x32_bf16(Bt[n][k], At[m][k], acc[ai][bj][m][n], 0, 0, 0); __builtin_amdgcn_s_setprio(0); } while (0)
; #define PG8_WAIT_V(n) asm volatile("s_waitcnt vmcnt(" #n ")" ::: "memory")
; #define PG8_WAIT_L(n) asm volatile("s_waitcnt lgkmcnt(" #n ")" ::: "memory")
; #define PG8_BAR __builtin_amdgcn_s_barrier()
; #define PG8_SCHED __builtin_amdgcn_sched_barrier(0)
; template <class Epi, class Sched>
; __device__ __forceinline__ void gemm_phase(LAS unsigned char* lds, const Gemm g, const Sched& S, const Epi& E) {
;     ...
;             PG8_LDB(B0, 0, 0); PG8_SCHED; PG8_LDA(At, 0, 0); PG8_STAGE(PG8_SA(1, 1), a1 + hA, voffA);
;             PG8_WAIT_L(8); PG8_BAR; PG8_WAIT_L(0); PG8_MMA(0, 0, At, B0); PG8_BAR; PG8_SCHED;
;             PG8_LDB(B1, 0, 1); PG8_STAGE(PG8_SB(0, 0), b2, voffB);
;             PG8_BAR; PG8_WAIT_L(0); PG8_MMA(0, 1, At, B1); PG8_BAR;
;             PG8_LDA(At, 0, 1); PG8_STAGE(PG8_SA(0, 0), a2, voffA);
;             PG8_BAR; PG8_WAIT_L(0); PG8_MMA(1, 0, At, B0); PG8_BAR; PG8_SCHED;
;             PG8_STAGE(PG8_SB(0, 1), b2 + hB, voffB);
;             PG8_WAIT_V(6); PG8_BAR; PG8_MMA(1, 1, At, B1); PG8_BAR;
.LBB0_74:
	ds_read_b128 v[160:163], v154
	ds_read_b128 v[164:167], v154 offset:1024
	ds_read_b128 v[168:171], v154 offset:2048
	ds_read_b128 v[172:175], v154 offset:3072
	s_add_u32 s12, s10, 0x100
	s_addc_u32 s13, s11, 0
	s_cmp_eq_u32 s43, 12
	s_cselect_b32 s18, s6, s12
	s_cselect_b32 s19, s7, s13
	s_cselect_b32 s14, s40, s41
	s_cselect_b32 s15, s39, s42
	s_add_u32 s16, s18, 0x80
	s_addc_u32 s17, s19, 0
	s_add_u32 s10, s10, 0x40080
	s_addc_u32 s11, s11, 0
	s_mov_b32 m0, s28
	ds_read_b128 v[178:181], v155
	ds_read_b128 v[182:185], v155 offset:1024
	ds_read_b128 v[186:189], v155 offset:2048
	ds_read_b128 v[190:193], v155 offset:3072
	ds_read_b128 v[194:197], v155 offset:4096
	ds_read_b128 v[198:201], v155 offset:5120
	ds_read_b128 v[202:205], v155 offset:6144
	ds_read_b128 v[206:209], v155 offset:7168
	s_nop 0
	v_lshl_add_u64 v[210:211], s[10:11], 0, v[134:135]
	global_load_lds_dwordx4 v[210:211], off nt
	v_lshl_add_u64 v[210:211], s[10:11], 0, v[130:131]
	s_mov_b32 m0, s29
	s_nop 0
	global_load_lds_dwordx4 v[210:211], off nt
	s_waitcnt lgkmcnt(8)
	s_barrier
	s_waitcnt lgkmcnt(0)
	s_setprio 1
	s_waitcnt lgkmcnt(0)
	v_mfma_f32_16x16x32_bf16 v[124:127], v[160:163], v[178:181], v[124:127]
	v_mfma_f32_16x16x32_bf16 v[120:123], v[168:171], v[178:181], v[120:123]
	v_mfma_f32_16x16x32_bf16 v[116:119], v[160:163], v[186:189], v[116:119]
	v_mfma_f32_16x16x32_bf16 v[108:111], v[168:171], v[186:189], v[108:111]
	v_mfma_f32_16x16x32_bf16 v[100:103], v[160:163], v[194:197], v[100:103]
	v_mfma_f32_16x16x32_bf16 v[92:95], v[168:171], v[194:197], v[92:95]
	v_mfma_f32_16x16x32_bf16 v[84:87], v[160:163], v[202:205], v[84:87]
	v_mfma_f32_16x16x32_bf16 v[76:79], v[168:171], v[202:205], v[76:79]
	v_mfma_f32_16x16x32_bf16 v[124:127], v[164:167], v[182:185], v[124:127]
	v_mfma_f32_16x16x32_bf16 v[120:123], v[172:175], v[182:185], v[120:123]
	v_mfma_f32_16x16x32_bf16 v[116:119], v[164:167], v[190:193], v[116:119]
	v_mfma_f32_16x16x32_bf16 v[108:111], v[172:175], v[190:193], v[108:111]
	v_mfma_f32_16x16x32_bf16 v[100:103], v[164:167], v[198:201], v[100:103]
	v_mfma_f32_16x16x32_bf16 v[92:95], v[172:175], v[198:201], v[92:95]
	v_mfma_f32_16x16x32_bf16 v[84:87], v[164:167], v[206:209], v[84:87]
	v_mfma_f32_16x16x32_bf16 v[76:79], v[172:175], v[206:209], v[76:79]
	s_setprio 0
	s_barrier
	s_mov_b64 s[10:11], s[14:15]
	s_mov_b32 m0, s30
	ds_read_b128 v[210:213], v156
	ds_read_b128 v[214:217], v156 offset:1024
	ds_read_b128 v[218:221], v156 offset:2048
	ds_read_b128 v[222:225], v156 offset:3072
	s_nop 0
	v_lshl_add_u64 v[226:227], s[10:11], 0, v[132:133]
	global_load_lds_dwordx4 v[226:227], off
	v_lshl_add_u64 v[226:227], s[10:11], 0, v[128:129]
	s_mov_b32 m0, s31
	s_nop 0
	global_load_lds_dwordx4 v[226:227], off
	s_barrier
	s_waitcnt lgkmcnt(0)
	s_setprio 1
	s_waitcnt lgkmcnt(0)
	v_mfma_f32_16x16x32_bf16 v[112:115], v[210:213], v[178:181], v[112:115]
	v_mfma_f32_16x16x32_bf16 v[104:107], v[218:221], v[178:181], v[104:107]
	v_mfma_f32_16x16x32_bf16 v[96:99], v[210:213], v[186:189], v[96:99]
	v_mfma_f32_16x16x32_bf16 v[88:91], v[218:221], v[186:189], v[88:91]
	v_mfma_f32_16x16x32_bf16 v[80:83], v[210:213], v[194:197], v[80:83]
	v_mfma_f32_16x16x32_bf16 v[72:75], v[218:221], v[194:197], v[72:75]
	v_mfma_f32_16x16x32_bf16 v[68:71], v[210:213], v[202:205], v[68:71]
	v_mfma_f32_16x16x32_bf16 v[64:67], v[218:221], v[202:205], v[64:67]
	v_mfma_f32_16x16x32_bf16 v[112:115], v[214:217], v[182:185], v[112:115]
	v_mfma_f32_16x16x32_bf16 v[104:107], v[222:225], v[182:185], v[104:107]
	v_mfma_f32_16x16x32_bf16 v[96:99], v[214:217], v[190:193], v[96:99]
	v_mfma_f32_16x16x32_bf16 v[88:91], v[222:225], v[190:193], v[88:91]
	v_mfma_f32_16x16x32_bf16 v[80:83], v[214:217], v[198:201], v[80:83]
	v_mfma_f32_16x16x32_bf16 v[72:75], v[222:225], v[198:201], v[72:75]
	v_mfma_f32_16x16x32_bf16 v[68:71], v[214:217], v[206:209], v[68:71]
	v_mfma_f32_16x16x32_bf16 v[64:67], v[222:225], v[206:209], v[64:67]
	s_setprio 0
	s_mov_b64 s[10:11], s[18:19]
	s_mov_b32 m0, s3
	s_barrier
	ds_read_b128 v[178:181], v155 offset:16384
	ds_read_b128 v[182:185], v155 offset:17408
	ds_read_b128 v[186:189], v155 offset:18432
	ds_read_b128 v[190:193], v155 offset:19456
	ds_read_b128 v[194:197], v155 offset:20480
	ds_read_b128 v[198:201], v155 offset:21504
	ds_read_b128 v[202:205], v155 offset:22528
	ds_read_b128 v[206:209], v155 offset:23552
	s_nop 0
	v_lshl_add_u64 v[226:227], s[10:11], 0, v[134:135]
	global_load_lds_dwordx4 v[226:227], off nt
	v_lshl_add_u64 v[226:227], s[10:11], 0, v[130:131]
	s_mov_b32 m0, s22
	s_nop 0
	global_load_lds_dwordx4 v[226:227], off nt
	s_barrier
	s_waitcnt lgkmcnt(0)
	s_setprio 1
	s_waitcnt lgkmcnt(0)
	v_mfma_f32_16x16x32_bf16 v[60:63], v[160:163], v[178:181], v[60:63]
	v_mfma_f32_16x16x32_bf16 v[56:59], v[168:171], v[178:181], v[56:59]
	v_mfma_f32_16x16x32_bf16 v[52:55], v[160:163], v[186:189], v[52:55]
	v_mfma_f32_16x16x32_bf16 v[44:47], v[168:171], v[186:189], v[44:47]
	v_mfma_f32_16x16x32_bf16 v[36:39], v[160:163], v[194:197], v[36:39]
	v_mfma_f32_16x16x32_bf16 v[28:31], v[168:171], v[194:197], v[28:31]
	v_mfma_f32_16x16x32_bf16 v[20:23], v[160:163], v[202:205], v[20:23]
	v_mfma_f32_16x16x32_bf16 v[12:15], v[168:171], v[202:205], v[12:15]
	v_mfma_f32_16x16x32_bf16 v[60:63], v[164:167], v[182:185], v[60:63]
	v_mfma_f32_16x16x32_bf16 v[56:59], v[172:175], v[182:185], v[56:59]
	v_mfma_f32_16x16x32_bf16 v[52:55], v[164:167], v[190:193], v[52:55]
	v_mfma_f32_16x16x32_bf16 v[44:47], v[172:175], v[190:193], v[44:47]
	v_mfma_f32_16x16x32_bf16 v[36:39], v[164:167], v[198:201], v[36:39]
	v_mfma_f32_16x16x32_bf16 v[28:31], v[172:175], v[198:201], v[28:31]
	v_mfma_f32_16x16x32_bf16 v[20:23], v[164:167], v[206:209], v[20:23]
	v_mfma_f32_16x16x32_bf16 v[12:15], v[172:175], v[206:209], v[12:15]
	s_setprio 0
	s_barrier
; #define PG8_STAGE(bufoff, gbase, voff) do { const char* _gb = (const char*)(gbase); asm volatile("" : "+s"(_gb)); _Pragma("unroll") for (int _i = 0; _i < 2; ++_i) \
;         __builtin_amdgcn_global_load_lds((const unsigned*)(_gb + (voff)[_i]), (LAS unsigned*)(lds + (bufoff) + ldsw + _i * 8192), 16, 0, 0); } while (0)
; #define PG8_LDA(dst, b, h) do { _Pragma("unroll") for (int m = 0; m < 4; ++m) _Pragma("unroll") for (int k = 0; k < 2; ++k) dst[m][k] = *(const LAS bf16x8*)(lds + PG8_SA(b, h) + aoff + m * 2048 + k * 1024); } while (0)
; #define PG8_LDB(dst, b, h) do { _Pragma("unroll") for (int n = 0; n < 2; ++n) _Pragma("unroll") for (int k = 0; k < 2; ++k) dst[n][k] = *(const LAS bf16x8*)(lds + PG8_SB(b, h) + boff + n * 2048 + k * 1024); } while (0)
; #define PG8_MMA(ai, bj, At, Bt) do { __builtin_amdgcn_s_setprio(1); _Pragma("unroll") for (int m = 0; m < 4; ++m) _Pragma("unroll") for (int n = 0; n < 2; ++n) _Pragma("unroll") for (int k = 0; k < 2; ++k) \
;         acc[ai][bj][m][n] = __builtin_amdgcn_mfma_f32_16x16x32_bf16(Bt[n][k], At[m][k], acc[ai][bj][m][n], 0, 0, 0); __builtin_amdgcn_s_setprio(0); } while (0)
; #define PG8_WAIT_V(n) asm volatile("s_waitcnt vmcnt(" #n ")" ::: "memory")
; #define PG8_WAIT_L(n) asm volatile("s_waitcnt lgkmcnt(" #n ")" ::: "memory")
; #define PG8_BAR __builtin_amdgcn_s_barrier()
; #define PG8_SCHED __builtin_amdgcn_sched_barrier(0)
; template <class Epi, class Sched>
; __device__ __forceinline__ void gemm_phase(LAS unsigned char* lds, const Gemm g, const Sched& S, const Epi& E) {
;     ...
;             PG8_WAIT_V(6); PG8_BAR; PG8_MMA(1, 1, At, B1); PG8_BAR;
;             PG8_LDB(B0, 1, 0); PG8_SCHED; PG8_LDA(At, 1, 0); PG8_STAGE(PG8_SA(0, 1), a2 + hA, voffA);
;             PG8_WAIT_L(8); PG8_BAR; PG8_WAIT_L(0); PG8_MMA(0, 0, At, B0); PG8_BAR; PG8_SCHED;
;             PG8_LDB(B1, 1, 1); PG8_STAGE(PG8_SB(1, 0), b3, voffB);
;             PG8_BAR; PG8_WAIT_L(0); PG8_MMA(0, 1, At, B1); PG8_BAR;
;             PG8_LDA(At, 1, 1); PG8_STAGE(PG8_SA(1, 0), a3, voffA);
;             PG8_BAR; PG8_WAIT_L(0); PG8_MMA(1, 0, At, B0); PG8_BAR; PG8_SCHED;
	s_add_u32 s10, s14, 0x40000
	s_addc_u32 s11, s15, 0
	s_mov_b32 m0, s33
	s_nop 0
	v_lshl_add_u64 v[160:161], s[10:11], 0, v[132:133]
	global_load_lds_dwordx4 v[160:161], off
	v_lshl_add_u64 v[160:161], s[10:11], 0, v[128:129]
	s_mov_b32 m0, s34
	s_nop 0
	global_load_lds_dwordx4 v[160:161], off
	s_waitcnt vmcnt(6)
	s_barrier
	s_setprio 1
	v_mfma_f32_16x16x32_bf16 v[48:51], v[210:213], v[178:181], v[48:51]
	v_mfma_f32_16x16x32_bf16 v[40:43], v[218:221], v[178:181], v[40:43]
	v_mfma_f32_16x16x32_bf16 v[32:35], v[210:213], v[186:189], v[32:35]
	v_mfma_f32_16x16x32_bf16 v[24:27], v[218:221], v[186:189], v[24:27]
	v_mfma_f32_16x16x32_bf16 v[16:19], v[210:213], v[194:197], v[16:19]
	v_mfma_f32_16x16x32_bf16 v[8:11], v[218:221], v[194:197], v[8:11]
	v_mfma_f32_16x16x32_bf16 v[4:7], v[210:213], v[202:205], v[4:7]
	v_mfma_f32_16x16x32_bf16 v[0:3], v[218:221], v[202:205], v[0:3]
	v_mfma_f32_16x16x32_bf16 v[48:51], v[214:217], v[182:185], v[48:51]
	v_mfma_f32_16x16x32_bf16 v[40:43], v[222:225], v[182:185], v[40:43]
	v_mfma_f32_16x16x32_bf16 v[32:35], v[214:217], v[190:193], v[32:35]
	v_mfma_f32_16x16x32_bf16 v[24:27], v[222:225], v[190:193], v[24:27]
	v_mfma_f32_16x16x32_bf16 v[16:19], v[214:217], v[198:201], v[16:19]
	v_mfma_f32_16x16x32_bf16 v[8:11], v[222:225], v[198:201], v[8:11]
	v_mfma_f32_16x16x32_bf16 v[4:7], v[214:217], v[206:209], v[4:7]
	v_mfma_f32_16x16x32_bf16 v[0:3], v[222:225], v[206:209], v[0:3]
	s_setprio 0
	s_barrier
	ds_read_b128 v[160:163], v158
	ds_read_b128 v[164:167], v158 offset:1024
	ds_read_b128 v[168:171], v158 offset:2048
	ds_read_b128 v[172:175], v158 offset:3072
	s_add_u32 s10, s18, 0x40000
	s_addc_u32 s11, s19, 0
	s_mov_b32 m0, s23
	ds_read_b128 v[178:181], v155 offset:32768
	ds_read_b128 v[182:185], v155 offset:33792
	ds_read_b128 v[186:189], v155 offset:34816
	ds_read_b128 v[190:193], v155 offset:35840
	ds_read_b128 v[194:197], v155 offset:36864
	ds_read_b128 v[198:201], v155 offset:37888
	ds_read_b128 v[202:205], v155 offset:38912
	ds_read_b128 v[206:209], v155 offset:39936
	s_nop 0
	v_lshl_add_u64 v[210:211], s[10:11], 0, v[134:135]
	global_load_lds_dwordx4 v[210:211], off nt
	v_lshl_add_u64 v[210:211], s[10:11], 0, v[130:131]
	s_mov_b32 m0, s24
	s_nop 0
	global_load_lds_dwordx4 v[210:211], off nt
	s_waitcnt lgkmcnt(8)
	s_barrier
	s_waitcnt lgkmcnt(0)
	s_setprio 1
	s_waitcnt lgkmcnt(0)
	v_mfma_f32_16x16x32_bf16 v[124:127], v[160:163], v[178:181], v[124:127]
	v_mfma_f32_16x16x32_bf16 v[120:123], v[168:171], v[178:181], v[120:123]
	v_mfma_f32_16x16x32_bf16 v[116:119], v[160:163], v[186:189], v[116:119]
	v_mfma_f32_16x16x32_bf16 v[108:111], v[168:171], v[186:189], v[108:111]
	v_mfma_f32_16x16x32_bf16 v[100:103], v[160:163], v[194:197], v[100:103]
	v_mfma_f32_16x16x32_bf16 v[92:95], v[168:171], v[194:197], v[92:95]
	v_mfma_f32_16x16x32_bf16 v[84:87], v[160:163], v[202:205], v[84:87]
	v_mfma_f32_16x16x32_bf16 v[76:79], v[168:171], v[202:205], v[76:79]
	v_mfma_f32_16x16x32_bf16 v[124:127], v[164:167], v[182:185], v[124:127]
	v_mfma_f32_16x16x32_bf16 v[120:123], v[172:175], v[182:185], v[120:123]
	v_mfma_f32_16x16x32_bf16 v[116:119], v[164:167], v[190:193], v[116:119]
	v_mfma_f32_16x16x32_bf16 v[108:111], v[172:175], v[190:193], v[108:111]
	v_mfma_f32_16x16x32_bf16 v[100:103], v[164:167], v[198:201], v[100:103]
	v_mfma_f32_16x16x32_bf16 v[92:95], v[172:175], v[198:201], v[92:95]
	v_mfma_f32_16x16x32_bf16 v[84:87], v[164:167], v[206:209], v[84:87]
	v_mfma_f32_16x16x32_bf16 v[76:79], v[172:175], v[206:209], v[76:79]
	s_setprio 0
	s_barrier
	s_add_u32 s10, s14, 0x80
	s_addc_u32 s11, s15, 0
	s_add_i32 s18, s35, s21
	ds_read_b128 v[210:213], v159
	ds_read_b128 v[214:217], v159 offset:1024
	ds_read_b128 v[218:221], v159 offset:2048
	ds_read_b128 v[222:225], v159 offset:3072
	s_mov_b32 m0, s18
	v_lshl_add_u64 v[226:227], s[10:11], 0, v[132:133]
	global_load_lds_dwordx4 v[226:227], off
	v_lshl_add_u64 v[226:227], s[10:11], 0, v[128:129]
	s_add_i32 m0, s18, 0x2000
	s_nop 0
	global_load_lds_dwordx4 v[226:227], off
	s_barrier
	s_waitcnt lgkmcnt(0)
	s_setprio 1
	s_waitcnt lgkmcnt(0)
	v_mfma_f32_16x16x32_bf16 v[112:115], v[210:213], v[178:181], v[112:115]
	v_mfma_f32_16x16x32_bf16 v[104:107], v[218:221], v[178:181], v[104:107]
	v_mfma_f32_16x16x32_bf16 v[96:99], v[210:213], v[186:189], v[96:99]
	v_mfma_f32_16x16x32_bf16 v[88:91], v[218:221], v[186:189], v[88:91]
	v_mfma_f32_16x16x32_bf16 v[80:83], v[210:213], v[194:197], v[80:83]
	v_mfma_f32_16x16x32_bf16 v[72:75], v[218:221], v[194:197], v[72:75]
	v_mfma_f32_16x16x32_bf16 v[68:71], v[210:213], v[202:205], v[68:71]
	v_mfma_f32_16x16x32_bf16 v[64:67], v[218:221], v[202:205], v[64:67]
	v_mfma_f32_16x16x32_bf16 v[112:115], v[214:217], v[182:185], v[112:115]
	v_mfma_f32_16x16x32_bf16 v[104:107], v[222:225], v[182:185], v[104:107]
	v_mfma_f32_16x16x32_bf16 v[96:99], v[214:217], v[190:193], v[96:99]
	v_mfma_f32_16x16x32_bf16 v[88:91], v[222:225], v[190:193], v[88:91]
	v_mfma_f32_16x16x32_bf16 v[80:83], v[214:217], v[198:201], v[80:83]
	v_mfma_f32_16x16x32_bf16 v[72:75], v[222:225], v[198:201], v[72:75]
	v_mfma_f32_16x16x32_bf16 v[68:71], v[214:217], v[206:209], v[68:71]
	v_mfma_f32_16x16x32_bf16 v[64:67], v[222:225], v[206:209], v[64:67]
	s_setprio 0
	s_mov_b32 m0, s25
	s_barrier
	ds_read_b128 v[178:181], v155 offset:49152
	ds_read_b128 v[182:185], v155 offset:50176
	ds_read_b128 v[186:189], v155 offset:51200
	ds_read_b128 v[190:193], v155 offset:52224
	ds_read_b128 v[194:197], v155 offset:53248
	ds_read_b128 v[198:201], v155 offset:54272
	ds_read_b128 v[202:205], v155 offset:55296
	ds_read_b128 v[206:209], v155 offset:56320
	s_nop 0
	v_lshl_add_u64 v[226:227], s[16:17], 0, v[134:135]
	global_load_lds_dwordx4 v[226:227], off
	v_lshl_add_u64 v[226:227], s[16:17], 0, v[130:131]
	s_mov_b32 m0, s26
	s_nop 0
	global_load_lds_dwordx4 v[226:227], off
	s_barrier
; __device__ __forceinline__ unsigned cvt_pk(float lo, float hi) { unsigned r; asm volatile("v_cvt_pk_bf16_f32 %0, %1, %2" : "=v"(r) : "v"(lo), "v"(hi)); return r; }
; #define PG8_STAGE(bufoff, gbase, voff) do { const char* _gb = (const char*)(gbase); asm volatile("" : "+s"(_gb)); _Pragma("unroll") for (int _i = 0; _i < 2; ++_i) \
;         __builtin_amdgcn_global_load_lds((const unsigned*)(_gb + (voff)[_i]), (LAS unsigned*)(lds + (bufoff) + ldsw + _i * 8192), 16, 0, 0); } while (0)
; #define PG8_MMA(ai, bj, At, Bt) do { __builtin_amdgcn_s_setprio(1); _Pragma("unroll") for (int m = 0; m < 4; ++m) _Pragma("unroll") for (int n = 0; n < 2; ++n) _Pragma("unroll") for (int k = 0; k < 2; ++k) \
;         acc[ai][bj][m][n] = __builtin_amdgcn_mfma_f32_16x16x32_bf16(Bt[n][k], At[m][k], acc[ai][bj][m][n], 0, 0, 0); __builtin_amdgcn_s_setprio(0); } while (0)
; #define PG8_WAIT_V(n) asm volatile("s_waitcnt vmcnt(" #n ")" ::: "memory")
; #define PG8_WAIT_L(n) asm volatile("s_waitcnt lgkmcnt(" #n ")" ::: "memory")
; #define PG8_BAR __builtin_amdgcn_s_barrier()
; #define PG8_SCHED __builtin_amdgcn_sched_barrier(0)
; template <class Epi, class Sched>
; __device__ __forceinline__ void gemm_phase(LAS unsigned char* lds, const Gemm g, const Sched& S, const Epi& E) {
;     ...
;             PG8_BAR; PG8_WAIT_L(0); PG8_MMA(1, 0, At, B0); PG8_BAR; PG8_SCHED;
;             PG8_STAGE(PG8_SB(1, 1), b3 + hB, voffB);
;             PG8_WAIT_V(6); PG8_BAR; PG8_MMA(1, 1, At, B1); PG8_BAR;
;         }
;         E(acc, cur, wr, wc, fr, fq);
;     __device__ __forceinline__ void operator()(const f32x4 (&acc)[2][2][4][2], const Unit& u, int wr, int wc, int fr, int fq) const {
;         const int row0 = u.pm * BM + wr * 64 + fr;
;         if (u.pn < 12) {
;             const int col0 = u.pn * BM + wc * 32 + 8 * fq;
; #pragma unroll
;             for (int ai = 0; ai < 2; ++ai)
; #pragma unroll
;                 for (int m = 0; m < 4; ++m) { bf16_t* rowp = P0 + (size_t)(row0 + ai * HALF + m * 16) * LDP + col0;
; #pragma unroll
;                     for (int bj = 0; bj < 2; ++bj) { const f32x4 v0 = acc[ai][bj][m][0], v1 = acc[ai][bj][m][1];
;                         u32x4 w; w.x = cvt_pk(v0[0], v0[1]); w.y = cvt_pk(v0[2], v0[3]); w.z = cvt_pk(v1[0], v1[1]); w.w = cvt_pk(v1[2], v1[3]);
;                         *(u32x4*)(rowp + bj * HALF) = w; } }
	s_waitcnt lgkmcnt(0)
	s_setprio 1
	s_waitcnt lgkmcnt(0)
	v_mfma_f32_16x16x32_bf16 v[60:63], v[160:163], v[178:181], v[60:63]
	v_mfma_f32_16x16x32_bf16 v[56:59], v[168:171], v[178:181], v[56:59]
	v_mfma_f32_16x16x32_bf16 v[52:55], v[160:163], v[186:189], v[52:55]
	v_mfma_f32_16x16x32_bf16 v[44:47], v[168:171], v[186:189], v[44:47]
	v_mfma_f32_16x16x32_bf16 v[36:39], v[160:163], v[194:197], v[36:39]
	v_mfma_f32_16x16x32_bf16 v[28:31], v[168:171], v[194:197], v[28:31]
	v_mfma_f32_16x16x32_bf16 v[20:23], v[160:163], v[202:205], v[20:23]
	v_mfma_f32_16x16x32_bf16 v[12:15], v[168:171], v[202:205], v[12:15]
	v_mfma_f32_16x16x32_bf16 v[60:63], v[164:167], v[182:185], v[60:63]
	v_mfma_f32_16x16x32_bf16 v[56:59], v[172:175], v[182:185], v[56:59]
	v_mfma_f32_16x16x32_bf16 v[52:55], v[164:167], v[190:193], v[52:55]
	v_mfma_f32_16x16x32_bf16 v[44:47], v[172:175], v[190:193], v[44:47]
	v_mfma_f32_16x16x32_bf16 v[36:39], v[164:167], v[198:201], v[36:39]
	v_mfma_f32_16x16x32_bf16 v[28:31], v[172:175], v[198:201], v[28:31]
	v_mfma_f32_16x16x32_bf16 v[20:23], v[164:167], v[206:209], v[20:23]
	v_mfma_f32_16x16x32_bf16 v[12:15], v[172:175], v[206:209], v[12:15]
	s_setprio 0
	s_barrier
	s_add_u32 s10, s14, 0x40080
	s_addc_u32 s11, s15, 0
	s_add_i32 s14, s36, s21
	s_mov_b32 m0, s14
	v_lshl_add_u64 v[160:161], s[10:11], 0, v[132:133]
	global_load_lds_dwordx4 v[160:161], off
	v_lshl_add_u64 v[160:161], s[10:11], 0, v[128:129]
	s_add_i32 m0, s14, 0x2000
	s_nop 0
	global_load_lds_dwordx4 v[160:161], off
	s_waitcnt vmcnt(6)
	s_barrier
	s_setprio 1
	v_mfma_f32_16x16x32_bf16 v[48:51], v[210:213], v[178:181], v[48:51]
	v_mfma_f32_16x16x32_bf16 v[40:43], v[218:221], v[178:181], v[40:43]
	v_mfma_f32_16x16x32_bf16 v[32:35], v[210:213], v[186:189], v[32:35]
	v_mfma_f32_16x16x32_bf16 v[24:27], v[218:221], v[186:189], v[24:27]
	v_mfma_f32_16x16x32_bf16 v[16:19], v[210:213], v[194:197], v[16:19]
	v_mfma_f32_16x16x32_bf16 v[8:11], v[218:221], v[194:197], v[8:11]
	v_mfma_f32_16x16x32_bf16 v[4:7], v[210:213], v[202:205], v[4:7]
	v_mfma_f32_16x16x32_bf16 v[0:3], v[218:221], v[202:205], v[0:3]
	v_mfma_f32_16x16x32_bf16 v[48:51], v[214:217], v[182:185], v[48:51]
	v_mfma_f32_16x16x32_bf16 v[40:43], v[222:225], v[182:185], v[40:43]
	v_mfma_f32_16x16x32_bf16 v[32:35], v[214:217], v[190:193], v[32:35]
	v_mfma_f32_16x16x32_bf16 v[24:27], v[222:225], v[190:193], v[24:27]
	v_mfma_f32_16x16x32_bf16 v[16:19], v[214:217], v[198:201], v[16:19]
	v_mfma_f32_16x16x32_bf16 v[8:11], v[222:225], v[198:201], v[8:11]
	v_mfma_f32_16x16x32_bf16 v[4:7], v[214:217], v[206:209], v[4:7]
	v_mfma_f32_16x16x32_bf16 v[0:3], v[222:225], v[206:209], v[0:3]
	s_setprio 0
	s_add_i32 s43, s43, 2
	s_add_u32 s41, s41, 0x100
	s_addc_u32 s42, s42, 0
	s_cmp_gt_u32 s43, 13
	s_mov_b64 s[10:11], s[12:13]
	s_barrier
	s_cbranch_scc0 .LBB0_74
	v_lshl_or_b32 v136, s38, 9, v157
	v_lshl_add_u64 v[160:161], v[138:139], 0, v[136:137]
	v_cvt_pk_bf16_f32 v124, v124, v125
	v_cvt_pk_bf16_f32 v125, v126, v127
	v_cvt_pk_bf16_f32 v126, v120, v121
	v_cvt_pk_bf16_f32 v127, v122, v123
	global_store_dwordx4 v[160:161], v[124:127], off sc1
	v_cvt_pk_bf16_f32 v112, v112, v113
	v_cvt_pk_bf16_f32 v113, v114, v115
	v_cvt_pk_bf16_f32 v114, v104, v105
	v_cvt_pk_bf16_f32 v115, v106, v107
	global_store_dwordx4 v[160:161], v[112:115], off offset:256 sc1
	v_cvt_pk_bf16_f32 v104, v116, v117
	v_cvt_pk_bf16_f32 v105, v118, v119
	v_cvt_pk_bf16_f32 v106, v108, v109
	v_cvt_pk_bf16_f32 v107, v110, v111
	s_cmp_eq_u32 s37, 12
	s_nop 0
	v_lshl_add_u64 v[112:113], v[140:141], 0, v[136:137]
	global_store_dwordx4 v[112:113], v[104:107], off sc1
	v_cvt_pk_bf16_f32 v96, v96, v97
	v_cvt_pk_bf16_f32 v97, v98, v99
	v_cvt_pk_bf16_f32 v98, v88, v89
	v_cvt_pk_bf16_f32 v99, v90, v91
	global_store_dwordx4 v[112:113], v[96:99], off offset:256 sc1
	v_cvt_pk_bf16_f32 v88, v100, v101
	v_cvt_pk_bf16_f32 v89, v102, v103
	v_cvt_pk_bf16_f32 v90, v92, v93
	v_cvt_pk_bf16_f32 v91, v94, v95
	s_mov_b32 s38, s37
	s_nop 0
	v_lshl_add_u64 v[96:97], v[142:143], 0, v[136:137]
	global_store_dwordx4 v[96:97], v[88:91], off sc1
	v_cvt_pk_bf16_f32 v80, v80, v81
	v_cvt_pk_bf16_f32 v81, v82, v83
	v_cvt_pk_bf16_f32 v82, v72, v73
	v_cvt_pk_bf16_f32 v83, v74, v75
	global_store_dwordx4 v[96:97], v[80:83], off offset:256 sc1
	v_cvt_pk_bf16_f32 v72, v84, v85
	v_cvt_pk_bf16_f32 v73, v86, v87
	v_cvt_pk_bf16_f32 v74, v76, v77
	v_cvt_pk_bf16_f32 v75, v78, v79
	s_mov_b64 s[10:11], s[8:9]
	s_nop 0
	v_lshl_add_u64 v[80:81], v[144:145], 0, v[136:137]
	global_store_dwordx4 v[80:81], v[72:75], off sc1
	v_cvt_pk_bf16_f32 v68, v68, v69
	v_cvt_pk_bf16_f32 v69, v70, v71
	v_cvt_pk_bf16_f32 v70, v64, v65
	v_lshl_add_u64 v[64:65], v[146:147], 0, v[136:137]
	v_cvt_pk_bf16_f32 v71, v66, v67
	global_store_dwordx4 v[80:81], v[68:71], off offset:256 sc1
	v_cvt_pk_bf16_f32 v60, v60, v61
	v_cvt_pk_bf16_f32 v61, v62, v63
	v_cvt_pk_bf16_f32 v62, v56, v57
	v_cvt_pk_bf16_f32 v63, v58, v59
	global_store_dwordx4 v[64:65], v[60:63], off sc1
	v_cvt_pk_bf16_f32 v48, v48, v49
	v_cvt_pk_bf16_f32 v49, v50, v51
	v_cvt_pk_bf16_f32 v50, v40, v41
	v_cvt_pk_bf16_f32 v51, v42, v43
	global_store_dwordx4 v[64:65], v[48:51], off offset:256 sc1
	v_cvt_pk_bf16_f32 v40, v52, v53
	v_cvt_pk_bf16_f32 v41, v54, v55
	v_cvt_pk_bf16_f32 v42, v44, v45
	v_cvt_pk_bf16_f32 v43, v46, v47
	s_nop 1
	v_lshl_add_u64 v[48:49], v[148:149], 0, v[136:137]
	global_store_dwordx4 v[48:49], v[40:43], off sc1
	v_cvt_pk_bf16_f32 v32, v32, v33
	v_cvt_pk_bf16_f32 v33, v34, v35
	v_cvt_pk_bf16_f32 v34, v24, v25
	v_cvt_pk_bf16_f32 v35, v26, v27
	global_store_dwordx4 v[48:49], v[32:35], off offset:256 sc1
	v_cvt_pk_bf16_f32 v24, v36, v37
	v_cvt_pk_bf16_f32 v25, v38, v39
	v_cvt_pk_bf16_f32 v26, v28, v29
	v_cvt_pk_bf16_f32 v27, v30, v31
	s_nop 1
	v_lshl_add_u64 v[32:33], v[150:151], 0, v[136:137]
	global_store_dwordx4 v[32:33], v[24:27], off sc1
	v_cvt_pk_bf16_f32 v16, v16, v17
	v_cvt_pk_bf16_f32 v17, v18, v19
	v_cvt_pk_bf16_f32 v18, v8, v9
	v_cvt_pk_bf16_f32 v19, v10, v11
	global_store_dwordx4 v[32:33], v[16:19], off offset:256 sc1
	v_cvt_pk_bf16_f32 v8, v20, v21
	v_cvt_pk_bf16_f32 v9, v22, v23
	v_cvt_pk_bf16_f32 v10, v12, v13
	v_cvt_pk_bf16_f32 v11, v14, v15
	s_nop 1
	v_lshl_add_u64 v[16:17], v[152:153], 0, v[136:137]
	global_store_dwordx4 v[16:17], v[8:11], off sc1
	v_cvt_pk_bf16_f32 v4, v4, v5
	v_cvt_pk_bf16_f32 v5, v6, v7
	v_cvt_pk_bf16_f32 v6, v0, v1
	v_cvt_pk_bf16_f32 v7, v2, v3
	global_store_dwordx4 v[16:17], v[4:7], off offset:256 sc1
	s_cbranch_scc0 .LBB0_73
	s_waitcnt vmcnt(0)
	s_cmpk_gt_u32 s20, 0xff
	s_cbranch_scc1 .LBB0_78
	s_barrier
